# K-loop MFMAs reordered so each accumulator's k0/k1 MFMAs are adjacent (SrcC forwarding chain) on top of early barrier
# speedup vs baseline: 1.0091x; 1.0078x over previous
.LBB0_262:
	s_add_u32 s2, s0, 0xfff80080
	s_addc_u32 s3, s1, -1
	s_add_i32 s6, 0, 0x10000
	s_cmp_eq_u32 s48, 28
	s_cselect_b32 s9, s25, s3
	s_cselect_b32 s8, s33, s2
	s_cselect_b32 s5, s39, s47
	s_cselect_b32 s4, s41, s46
	s_add_i32 s7, 0, 0x14000
	v_add_u32_e32 v174, s6, v10
	v_add_u32_e32 v190, s7, v10
	ds_read_b128 v[146:149], v174
	ds_read_b128 v[166:169], v174 offset:1024
	ds_read_b128 v[170:173], v174 offset:2048
	ds_read_b128 v[174:177], v174 offset:3072
	ds_read_b128 v[178:181], v190
	ds_read_b128 v[182:185], v190 offset:1024
	ds_read_b128 v[186:189], v190 offset:2048
	ds_read_b128 v[190:193], v190 offset:3072
	v_lshl_add_u64 v[212:213], s[0:1], 0, v[142:143]
	s_add_i32 m0, s15, 0xc000
	ds_read_b128 v[194:197], v161
	ds_read_b128 v[198:201], v161 offset:1024
	ds_read_b128 v[202:205], v161 offset:2048
	ds_read_b128 v[228:231], v161 offset:3072
	ds_read_b128 v[232:235], v161 offset:4096
	ds_read_b128 v[236:239], v161 offset:5120
	ds_read_b128 v[240:243], v161 offset:6144
	ds_read_b128 v[244:247], v161 offset:7168
	global_load_lds_dwordx4 v[212:213], off
	v_lshl_add_u64 v[212:213], s[0:1], 0, v[144:145]
	s_add_i32 m0, s15, 0xe000
	s_nop 0
	global_load_lds_dwordx4 v[212:213], off
	s_waitcnt vmcnt(8)
	s_waitcnt lgkmcnt(0)
	s_barrier
	s_setprio 1
	s_waitcnt lgkmcnt(0)
	v_mfma_f32_16x16x32_bf16 v[128:131], v[146:149], v[194:197], v[128:131]
	v_mfma_f32_16x16x32_bf16 v[128:131], v[166:169], v[198:201], v[128:131]
	v_mfma_f32_16x16x32_bf16 v[124:127], v[170:173], v[194:197], v[124:127]
	v_mfma_f32_16x16x32_bf16 v[124:127], v[174:177], v[198:201], v[124:127]
	v_mfma_f32_16x16x32_bf16 v[112:115], v[146:149], v[202:205], v[112:115]
	v_mfma_f32_16x16x32_bf16 v[112:115], v[166:169], v[228:231], v[112:115]
	v_mfma_f32_16x16x32_bf16 v[108:111], v[170:173], v[202:205], v[108:111]
	v_mfma_f32_16x16x32_bf16 v[108:111], v[174:177], v[228:231], v[108:111]
	v_mfma_f32_16x16x32_bf16 v[96:99], v[146:149], v[232:235], v[96:99]
	v_mfma_f32_16x16x32_bf16 v[96:99], v[166:169], v[236:239], v[96:99]
	v_mfma_f32_16x16x32_bf16 v[92:95], v[170:173], v[232:235], v[92:95]
	v_mfma_f32_16x16x32_bf16 v[92:95], v[174:177], v[236:239], v[92:95]
	v_mfma_f32_16x16x32_bf16 v[80:83], v[146:149], v[240:243], v[80:83]
	v_mfma_f32_16x16x32_bf16 v[80:83], v[166:169], v[244:247], v[80:83]
	v_mfma_f32_16x16x32_bf16 v[76:79], v[170:173], v[240:243], v[76:79]
	v_mfma_f32_16x16x32_bf16 v[76:79], v[174:177], v[244:247], v[76:79]
	s_setprio 0
	s_setprio 1
	v_mfma_f32_16x16x32_bf16 v[120:123], v[178:181], v[194:197], v[120:123]
	v_mfma_f32_16x16x32_bf16 v[120:123], v[182:185], v[198:201], v[120:123]
	v_mfma_f32_16x16x32_bf16 v[116:119], v[186:189], v[194:197], v[116:119]
	v_mfma_f32_16x16x32_bf16 v[116:119], v[190:193], v[198:201], v[116:119]
	v_mfma_f32_16x16x32_bf16 v[104:107], v[178:181], v[202:205], v[104:107]
	v_mfma_f32_16x16x32_bf16 v[104:107], v[182:185], v[228:231], v[104:107]
	v_mfma_f32_16x16x32_bf16 v[100:103], v[186:189], v[202:205], v[100:103]
	v_mfma_f32_16x16x32_bf16 v[100:103], v[190:193], v[228:231], v[100:103]
	v_mfma_f32_16x16x32_bf16 v[88:91], v[178:181], v[232:235], v[88:91]
	v_mfma_f32_16x16x32_bf16 v[88:91], v[182:185], v[236:239], v[88:91]
	v_mfma_f32_16x16x32_bf16 v[84:87], v[186:189], v[232:235], v[84:87]
	v_mfma_f32_16x16x32_bf16 v[84:87], v[190:193], v[236:239], v[84:87]
	s_setprio 2
	s_barrier
	v_mfma_f32_16x16x32_bf16 v[72:75], v[178:181], v[240:243], v[72:75]
	v_mfma_f32_16x16x32_bf16 v[72:75], v[182:185], v[244:247], v[72:75]
	v_mfma_f32_16x16x32_bf16 v[68:71], v[186:189], v[240:243], v[68:71]
	v_mfma_f32_16x16x32_bf16 v[68:71], v[190:193], v[244:247], v[68:71]
	s_setprio 0
	s_add_i32 s2, s6, s14
	v_lshl_add_u64 v[212:213], s[4:5], 0, v[136:137]
	s_mov_b32 m0, s2
	ds_read_b128 v[194:197], v161 offset:16384
	ds_read_b128 v[198:201], v161 offset:17408
	ds_read_b128 v[202:205], v161 offset:18432
	ds_read_b128 v[228:231], v161 offset:19456
	ds_read_b128 v[232:235], v161 offset:20480
	ds_read_b128 v[236:239], v161 offset:21504
	ds_read_b128 v[240:243], v161 offset:22528
	ds_read_b128 v[244:247], v161 offset:23552
	global_load_lds_dwordx4 v[212:213], off
	s_add_i32 m0, s2, 0x2000
	s_add_u32 s2, s4, 0x80000
	v_lshl_add_u64 v[214:215], s[4:5], 0, v[132:133]
	s_addc_u32 s3, s5, 0
	s_add_i32 s6, s7, s14
	global_load_lds_dwordx4 v[214:215], off
	v_lshl_add_u64 v[248:249], s[2:3], 0, v[136:137]
	s_mov_b32 m0, s6
	v_lshl_add_u64 v[216:217], s[8:9], 0, v[134:135]
	global_load_lds_dwordx4 v[248:249], off
	v_lshl_add_u64 v[248:249], s[2:3], 0, v[132:133]
	s_add_i32 m0, s6, 0x2000
	s_nop 0
	global_load_lds_dwordx4 v[248:249], off
	v_lshl_add_u64 v[248:249], s[8:9], 0, v[138:139]
	s_mov_b32 m0, s15
	s_nop 0
	global_load_lds_dwordx4 v[248:249], off
	s_mov_b32 m0, s18
	s_nop 0
	global_load_lds_dwordx4 v[216:217], off
	s_waitcnt vmcnt(8)
	s_waitcnt lgkmcnt(0)
	s_barrier
	s_setprio 1
	s_waitcnt lgkmcnt(0)
	v_mfma_f32_16x16x32_bf16 v[64:67], v[146:149], v[194:197], v[64:67]
	v_mfma_f32_16x16x32_bf16 v[64:67], v[166:169], v[198:201], v[64:67]
	v_mfma_f32_16x16x32_bf16 v[60:63], v[170:173], v[194:197], v[60:63]
	v_mfma_f32_16x16x32_bf16 v[60:63], v[174:177], v[198:201], v[60:63]
	v_mfma_f32_16x16x32_bf16 v[48:51], v[146:149], v[202:205], v[48:51]
	v_mfma_f32_16x16x32_bf16 v[48:51], v[166:169], v[228:231], v[48:51]
	v_mfma_f32_16x16x32_bf16 v[44:47], v[170:173], v[202:205], v[44:47]
	v_mfma_f32_16x16x32_bf16 v[44:47], v[174:177], v[228:231], v[44:47]
	v_mfma_f32_16x16x32_bf16 v[32:35], v[146:149], v[232:235], v[32:35]
	v_mfma_f32_16x16x32_bf16 v[32:35], v[166:169], v[236:239], v[32:35]
	v_mfma_f32_16x16x32_bf16 v[28:31], v[170:173], v[232:235], v[28:31]
	v_mfma_f32_16x16x32_bf16 v[28:31], v[174:177], v[236:239], v[28:31]
	v_mfma_f32_16x16x32_bf16 v[16:19], v[146:149], v[240:243], v[16:19]
	v_mfma_f32_16x16x32_bf16 v[16:19], v[166:169], v[244:247], v[16:19]
	v_mfma_f32_16x16x32_bf16 v[12:15], v[170:173], v[240:243], v[12:15]
	v_mfma_f32_16x16x32_bf16 v[12:15], v[174:177], v[244:247], v[12:15]
	s_setprio 0
	s_setprio 1
	v_mfma_f32_16x16x32_bf16 v[56:59], v[178:181], v[194:197], v[56:59]
	v_mfma_f32_16x16x32_bf16 v[56:59], v[182:185], v[198:201], v[56:59]
	v_mfma_f32_16x16x32_bf16 v[52:55], v[186:189], v[194:197], v[52:55]
	v_mfma_f32_16x16x32_bf16 v[52:55], v[190:193], v[198:201], v[52:55]
	v_mfma_f32_16x16x32_bf16 v[40:43], v[178:181], v[202:205], v[40:43]
	v_mfma_f32_16x16x32_bf16 v[40:43], v[182:185], v[228:231], v[40:43]
	v_mfma_f32_16x16x32_bf16 v[36:39], v[186:189], v[202:205], v[36:39]
	v_mfma_f32_16x16x32_bf16 v[36:39], v[190:193], v[228:231], v[36:39]
	v_mfma_f32_16x16x32_bf16 v[24:27], v[178:181], v[232:235], v[24:27]
	v_mfma_f32_16x16x32_bf16 v[24:27], v[182:185], v[236:239], v[24:27]
	v_mfma_f32_16x16x32_bf16 v[20:23], v[186:189], v[232:235], v[20:23]
	v_mfma_f32_16x16x32_bf16 v[20:23], v[190:193], v[236:239], v[20:23]
	s_setprio 2
	s_barrier
	v_mfma_f32_16x16x32_bf16 v[6:9], v[178:181], v[240:243], v[6:9]
	v_mfma_f32_16x16x32_bf16 v[6:9], v[182:185], v[244:247], v[6:9]
	v_mfma_f32_16x16x32_bf16 v[2:5], v[186:189], v[240:243], v[2:5]
	v_mfma_f32_16x16x32_bf16 v[2:5], v[190:193], v[244:247], v[2:5]
	s_setprio 0
	s_add_i32 s6, 0, 0x18000
	s_add_i32 s7, 0, 0x1c000
	v_add_u32_e32 v174, s6, v10
	v_add_u32_e32 v190, s7, v10
	ds_read_b128 v[146:149], v174
	ds_read_b128 v[166:169], v174 offset:1024
	ds_read_b128 v[170:173], v174 offset:2048
	ds_read_b128 v[174:177], v174 offset:3072
	ds_read_b128 v[178:181], v190
	ds_read_b128 v[182:185], v190 offset:1024
	ds_read_b128 v[186:189], v190 offset:2048
	ds_read_b128 v[190:193], v190 offset:3072
	s_add_u32 s2, s8, 0x80000
	s_addc_u32 s3, s9, 0
	s_mov_b32 m0, s19
	v_lshl_add_u64 v[218:219], s[2:3], 0, v[138:139]
	ds_read_b128 v[194:197], v161 offset:32768
	ds_read_b128 v[198:201], v161 offset:33792
	ds_read_b128 v[202:205], v161 offset:34816
	ds_read_b128 v[228:231], v161 offset:35840
	ds_read_b128 v[232:235], v161 offset:36864
	ds_read_b128 v[236:239], v161 offset:37888
	ds_read_b128 v[240:243], v161 offset:38912
	ds_read_b128 v[244:247], v161 offset:39936
	global_load_lds_dwordx4 v[218:219], off
	v_lshl_add_u64 v[218:219], s[2:3], 0, v[134:135]
	s_mov_b32 m0, s30
	s_nop 0
	global_load_lds_dwordx4 v[218:219], off
	s_waitcnt vmcnt(8)
	s_waitcnt lgkmcnt(0)
	s_barrier
	s_setprio 1
	s_waitcnt lgkmcnt(0)
	v_mfma_f32_16x16x32_bf16 v[128:131], v[146:149], v[194:197], v[128:131]
	v_mfma_f32_16x16x32_bf16 v[128:131], v[166:169], v[198:201], v[128:131]
	v_mfma_f32_16x16x32_bf16 v[124:127], v[170:173], v[194:197], v[124:127]
	v_mfma_f32_16x16x32_bf16 v[124:127], v[174:177], v[198:201], v[124:127]
	v_mfma_f32_16x16x32_bf16 v[112:115], v[146:149], v[202:205], v[112:115]
	v_mfma_f32_16x16x32_bf16 v[112:115], v[166:169], v[228:231], v[112:115]
	v_mfma_f32_16x16x32_bf16 v[108:111], v[170:173], v[202:205], v[108:111]
	v_mfma_f32_16x16x32_bf16 v[108:111], v[174:177], v[228:231], v[108:111]
	v_mfma_f32_16x16x32_bf16 v[96:99], v[146:149], v[232:235], v[96:99]
	v_mfma_f32_16x16x32_bf16 v[96:99], v[166:169], v[236:239], v[96:99]
	v_mfma_f32_16x16x32_bf16 v[92:95], v[170:173], v[232:235], v[92:95]
	v_mfma_f32_16x16x32_bf16 v[92:95], v[174:177], v[236:239], v[92:95]
	v_mfma_f32_16x16x32_bf16 v[80:83], v[146:149], v[240:243], v[80:83]
	v_mfma_f32_16x16x32_bf16 v[80:83], v[166:169], v[244:247], v[80:83]
	v_mfma_f32_16x16x32_bf16 v[76:79], v[170:173], v[240:243], v[76:79]
	v_mfma_f32_16x16x32_bf16 v[76:79], v[174:177], v[244:247], v[76:79]
	s_setprio 0
	s_setprio 1
	v_mfma_f32_16x16x32_bf16 v[120:123], v[178:181], v[194:197], v[120:123]
	v_mfma_f32_16x16x32_bf16 v[120:123], v[182:185], v[198:201], v[120:123]
	v_mfma_f32_16x16x32_bf16 v[116:119], v[186:189], v[194:197], v[116:119]
	v_mfma_f32_16x16x32_bf16 v[116:119], v[190:193], v[198:201], v[116:119]
	v_mfma_f32_16x16x32_bf16 v[104:107], v[178:181], v[202:205], v[104:107]
	v_mfma_f32_16x16x32_bf16 v[104:107], v[182:185], v[228:231], v[104:107]
	v_mfma_f32_16x16x32_bf16 v[100:103], v[186:189], v[202:205], v[100:103]
	v_mfma_f32_16x16x32_bf16 v[100:103], v[190:193], v[228:231], v[100:103]
	v_mfma_f32_16x16x32_bf16 v[88:91], v[178:181], v[232:235], v[88:91]
	v_mfma_f32_16x16x32_bf16 v[88:91], v[182:185], v[236:239], v[88:91]
	v_mfma_f32_16x16x32_bf16 v[84:87], v[186:189], v[232:235], v[84:87]
	v_mfma_f32_16x16x32_bf16 v[84:87], v[190:193], v[236:239], v[84:87]
	s_setprio 2
	s_barrier
	v_mfma_f32_16x16x32_bf16 v[72:75], v[178:181], v[240:243], v[72:75]
	v_mfma_f32_16x16x32_bf16 v[72:75], v[182:185], v[244:247], v[72:75]
	v_mfma_f32_16x16x32_bf16 v[68:71], v[186:189], v[240:243], v[68:71]
	v_mfma_f32_16x16x32_bf16 v[68:71], v[190:193], v[244:247], v[68:71]
	s_setprio 0
	s_add_i32 s2, s6, s14
	v_lshl_add_u64 v[212:213], v[212:213], 0, s[86:87]
	s_mov_b32 m0, s2
	ds_read_b128 v[194:197], v161 offset:49152
	ds_read_b128 v[198:201], v161 offset:50176
	ds_read_b128 v[202:205], v161 offset:51200
	ds_read_b128 v[228:231], v161 offset:52224
	ds_read_b128 v[232:235], v161 offset:53248
	ds_read_b128 v[236:239], v161 offset:54272
	ds_read_b128 v[240:243], v161 offset:55296
	ds_read_b128 v[244:247], v161 offset:56320
	global_load_lds_dwordx4 v[212:213], off
	s_add_i32 m0, s2, 0x2000
	s_add_u32 s2, s4, 0x80080
	v_lshl_add_u64 v[212:213], v[214:215], 0, s[86:87]
	s_addc_u32 s3, s5, 0
	s_add_i32 s4, s7, s14
	global_load_lds_dwordx4 v[212:213], off
	v_lshl_add_u64 v[212:213], s[2:3], 0, v[136:137]
	s_mov_b32 m0, s4
	s_nop 0
	global_load_lds_dwordx4 v[212:213], off
	v_lshl_add_u64 v[212:213], s[2:3], 0, v[132:133]
	s_add_i32 m0, s4, 0x2000
	s_nop 0
	global_load_lds_dwordx4 v[212:213], off
	v_lshl_add_u64 v[212:213], v[248:249], 0, s[86:87]
	s_mov_b32 m0, s31
	s_nop 0
	global_load_lds_dwordx4 v[212:213], off
	v_lshl_add_u64 v[212:213], v[216:217], 0, s[86:87]
	s_mov_b32 m0, s34
	s_nop 0
	global_load_lds_dwordx4 v[212:213], off
	s_waitcnt vmcnt(8)
	s_waitcnt lgkmcnt(0)
	s_barrier
	s_setprio 1
	s_waitcnt lgkmcnt(0)
	v_mfma_f32_16x16x32_bf16 v[64:67], v[146:149], v[194:197], v[64:67]
	v_mfma_f32_16x16x32_bf16 v[64:67], v[166:169], v[198:201], v[64:67]
	v_mfma_f32_16x16x32_bf16 v[60:63], v[170:173], v[194:197], v[60:63]
	v_mfma_f32_16x16x32_bf16 v[60:63], v[174:177], v[198:201], v[60:63]
	v_mfma_f32_16x16x32_bf16 v[48:51], v[146:149], v[202:205], v[48:51]
	v_mfma_f32_16x16x32_bf16 v[48:51], v[166:169], v[228:231], v[48:51]
	v_mfma_f32_16x16x32_bf16 v[44:47], v[170:173], v[202:205], v[44:47]
	v_mfma_f32_16x16x32_bf16 v[44:47], v[174:177], v[228:231], v[44:47]
	v_mfma_f32_16x16x32_bf16 v[32:35], v[146:149], v[232:235], v[32:35]
	v_mfma_f32_16x16x32_bf16 v[32:35], v[166:169], v[236:239], v[32:35]
	v_mfma_f32_16x16x32_bf16 v[28:31], v[170:173], v[232:235], v[28:31]
	v_mfma_f32_16x16x32_bf16 v[28:31], v[174:177], v[236:239], v[28:31]
	v_mfma_f32_16x16x32_bf16 v[16:19], v[146:149], v[240:243], v[16:19]
	v_mfma_f32_16x16x32_bf16 v[16:19], v[166:169], v[244:247], v[16:19]
	v_mfma_f32_16x16x32_bf16 v[12:15], v[170:173], v[240:243], v[12:15]
	v_mfma_f32_16x16x32_bf16 v[12:15], v[174:177], v[244:247], v[12:15]
	s_setprio 0
	s_setprio 1
	v_mfma_f32_16x16x32_bf16 v[56:59], v[178:181], v[194:197], v[56:59]
	v_mfma_f32_16x16x32_bf16 v[56:59], v[182:185], v[198:201], v[56:59]
	v_mfma_f32_16x16x32_bf16 v[52:55], v[186:189], v[194:197], v[52:55]
	v_mfma_f32_16x16x32_bf16 v[52:55], v[190:193], v[198:201], v[52:55]
	v_mfma_f32_16x16x32_bf16 v[40:43], v[178:181], v[202:205], v[40:43]
	v_mfma_f32_16x16x32_bf16 v[40:43], v[182:185], v[228:231], v[40:43]
	v_mfma_f32_16x16x32_bf16 v[36:39], v[186:189], v[202:205], v[36:39]
	v_mfma_f32_16x16x32_bf16 v[36:39], v[190:193], v[228:231], v[36:39]
	v_mfma_f32_16x16x32_bf16 v[24:27], v[178:181], v[232:235], v[24:27]
	v_mfma_f32_16x16x32_bf16 v[24:27], v[182:185], v[236:239], v[24:27]
	v_mfma_f32_16x16x32_bf16 v[20:23], v[186:189], v[232:235], v[20:23]
	v_mfma_f32_16x16x32_bf16 v[20:23], v[190:193], v[236:239], v[20:23]
	s_setprio 2
	s_barrier
	v_mfma_f32_16x16x32_bf16 v[6:9], v[178:181], v[240:243], v[6:9]
	v_mfma_f32_16x16x32_bf16 v[6:9], v[182:185], v[244:247], v[6:9]
	v_mfma_f32_16x16x32_bf16 v[2:5], v[186:189], v[240:243], v[2:5]
	v_mfma_f32_16x16x32_bf16 v[2:5], v[190:193], v[244:247], v[2:5]
	s_setprio 0
	s_add_i32 s48, s48, 2
	s_add_u32 s0, s0, 0x100
	s_addc_u32 s1, s1, 0
	s_add_u32 s46, s46, 0x100
	s_addc_u32 s47, s47, 0
	s_cmp_gt_u32 s48, 29
	s_cbranch_scc0 .LBB0_262
	s_and_b64 vcc, exec, s[28:29]
	s_cbranch_vccz .LBB0_265
	s_barrier

.LBB0_986:
	s_add_u32 s4, s0, 0x100
	s_addc_u32 s5, s1, 0
	s_add_i32 s2, 0, 0x10000
	s_cmpk_eq_i32 s49, 0x54
	s_cselect_b32 s11, s41, s5
	s_cselect_b32 s10, s40, s4
	v_add_u32_e32 v148, s2, v10
	s_cselect_b32 s9, s45, s48
	s_cselect_b32 s8, s44, s33
	s_add_i32 s3, 0, 0x14000
	ds_read_b128 v[144:147], v148
	ds_read_b128 v[166:169], v148 offset:1024
	ds_read_b128 v[170:173], v148 offset:2048
	ds_read_b128 v[174:177], v148 offset:3072
	v_add_u32_e32 v148, s3, v10
	ds_read_b128 v[178:181], v148
	ds_read_b128 v[182:185], v148 offset:1024
	ds_read_b128 v[186:189], v148 offset:2048
	ds_read_b128 v[190:193], v148 offset:3072
	v_lshl_add_u64 v[148:149], s[0:1], 0, v[140:141]
	s_add_i32 m0, s15, 0xc000
	ds_read_b128 v[194:197], v161
	ds_read_b128 v[198:201], v161 offset:1024
	ds_read_b128 v[202:205], v161 offset:2048
	ds_read_b128 v[228:231], v161 offset:3072
	ds_read_b128 v[232:235], v161 offset:4096
	ds_read_b128 v[236:239], v161 offset:5120
	ds_read_b128 v[240:243], v161 offset:6144
	ds_read_b128 v[244:247], v161 offset:7168
	global_load_lds_dwordx4 v[148:149], off
	v_lshl_add_u64 v[148:149], s[0:1], 0, v[142:143]
	s_add_i32 m0, s15, 0xe000
	s_nop 0
	global_load_lds_dwordx4 v[148:149], off
	s_waitcnt vmcnt(8)
	s_waitcnt lgkmcnt(0)
	s_barrier
	s_setprio 1
	s_waitcnt lgkmcnt(0)
	v_mfma_f32_16x16x32_bf16 v[128:131], v[144:147], v[194:197], v[128:131]
	v_mfma_f32_16x16x32_bf16 v[128:131], v[166:169], v[198:201], v[128:131]
	v_mfma_f32_16x16x32_bf16 v[124:127], v[170:173], v[194:197], v[124:127]
	v_mfma_f32_16x16x32_bf16 v[124:127], v[174:177], v[198:201], v[124:127]
	v_mfma_f32_16x16x32_bf16 v[112:115], v[144:147], v[202:205], v[112:115]
	v_mfma_f32_16x16x32_bf16 v[112:115], v[166:169], v[228:231], v[112:115]
	v_mfma_f32_16x16x32_bf16 v[108:111], v[170:173], v[202:205], v[108:111]
	v_mfma_f32_16x16x32_bf16 v[108:111], v[174:177], v[228:231], v[108:111]
	v_mfma_f32_16x16x32_bf16 v[96:99], v[144:147], v[232:235], v[96:99]
	v_mfma_f32_16x16x32_bf16 v[96:99], v[166:169], v[236:239], v[96:99]
	v_mfma_f32_16x16x32_bf16 v[92:95], v[170:173], v[232:235], v[92:95]
	v_mfma_f32_16x16x32_bf16 v[92:95], v[174:177], v[236:239], v[92:95]
	v_mfma_f32_16x16x32_bf16 v[80:83], v[144:147], v[240:243], v[80:83]
	v_mfma_f32_16x16x32_bf16 v[80:83], v[166:169], v[244:247], v[80:83]
	v_mfma_f32_16x16x32_bf16 v[76:79], v[170:173], v[240:243], v[76:79]
	v_mfma_f32_16x16x32_bf16 v[76:79], v[174:177], v[244:247], v[76:79]
	s_setprio 0
	s_setprio 1
	v_mfma_f32_16x16x32_bf16 v[120:123], v[178:181], v[194:197], v[120:123]
	v_mfma_f32_16x16x32_bf16 v[120:123], v[182:185], v[198:201], v[120:123]
	v_mfma_f32_16x16x32_bf16 v[116:119], v[186:189], v[194:197], v[116:119]
	v_mfma_f32_16x16x32_bf16 v[116:119], v[190:193], v[198:201], v[116:119]
	v_mfma_f32_16x16x32_bf16 v[104:107], v[178:181], v[202:205], v[104:107]
	v_mfma_f32_16x16x32_bf16 v[104:107], v[182:185], v[228:231], v[104:107]
	v_mfma_f32_16x16x32_bf16 v[100:103], v[186:189], v[202:205], v[100:103]
	v_mfma_f32_16x16x32_bf16 v[100:103], v[190:193], v[228:231], v[100:103]
	v_mfma_f32_16x16x32_bf16 v[88:91], v[178:181], v[232:235], v[88:91]
	v_mfma_f32_16x16x32_bf16 v[88:91], v[182:185], v[236:239], v[88:91]
	v_mfma_f32_16x16x32_bf16 v[84:87], v[186:189], v[232:235], v[84:87]
	v_mfma_f32_16x16x32_bf16 v[84:87], v[190:193], v[236:239], v[84:87]
	s_setprio 2
	s_barrier
	v_mfma_f32_16x16x32_bf16 v[72:75], v[178:181], v[240:243], v[72:75]
	v_mfma_f32_16x16x32_bf16 v[72:75], v[182:185], v[244:247], v[72:75]
	v_mfma_f32_16x16x32_bf16 v[68:71], v[186:189], v[240:243], v[68:71]
	v_mfma_f32_16x16x32_bf16 v[68:71], v[190:193], v[244:247], v[68:71]
	s_setprio 0
	s_add_i32 s0, s2, s14
	v_lshl_add_u64 v[148:149], s[8:9], 0, v[136:137]
	s_mov_b32 m0, s0
	ds_read_b128 v[194:197], v161 offset:16384
	ds_read_b128 v[198:201], v161 offset:17408
	ds_read_b128 v[202:205], v161 offset:18432
	ds_read_b128 v[228:231], v161 offset:19456
	ds_read_b128 v[232:235], v161 offset:20480
	ds_read_b128 v[236:239], v161 offset:21504
	ds_read_b128 v[240:243], v161 offset:22528
	ds_read_b128 v[244:247], v161 offset:23552
	global_load_lds_dwordx4 v[148:149], off
	s_add_i32 m0, s0, 0x2000
	s_add_u32 s0, s8, 0x160000
	v_lshl_add_u64 v[212:213], s[8:9], 0, v[132:133]
	s_addc_u32 s1, s9, 0
	s_add_i32 s2, s3, s14
	global_load_lds_dwordx4 v[212:213], off
	v_lshl_add_u64 v[214:215], s[0:1], 0, v[136:137]
	s_mov_b32 m0, s2
	v_lshl_add_u64 v[216:217], s[10:11], 0, v[134:135]
	global_load_lds_dwordx4 v[214:215], off
	v_lshl_add_u64 v[214:215], s[0:1], 0, v[132:133]
	s_add_i32 m0, s2, 0x2000
	s_nop 0
	global_load_lds_dwordx4 v[214:215], off
	v_lshl_add_u64 v[214:215], s[10:11], 0, v[138:139]
	s_mov_b32 m0, s15
	s_nop 0
	global_load_lds_dwordx4 v[214:215], off
	s_mov_b32 m0, s18
	s_nop 0
	global_load_lds_dwordx4 v[216:217], off
	s_waitcnt vmcnt(8)
	s_waitcnt lgkmcnt(0)
	s_barrier
	s_setprio 1
	s_waitcnt lgkmcnt(0)
	v_mfma_f32_16x16x32_bf16 v[64:67], v[144:147], v[194:197], v[64:67]
	v_mfma_f32_16x16x32_bf16 v[64:67], v[166:169], v[198:201], v[64:67]
	v_mfma_f32_16x16x32_bf16 v[60:63], v[170:173], v[194:197], v[60:63]
	v_mfma_f32_16x16x32_bf16 v[60:63], v[174:177], v[198:201], v[60:63]
	v_mfma_f32_16x16x32_bf16 v[48:51], v[144:147], v[202:205], v[48:51]
	v_mfma_f32_16x16x32_bf16 v[48:51], v[166:169], v[228:231], v[48:51]
	v_mfma_f32_16x16x32_bf16 v[44:47], v[170:173], v[202:205], v[44:47]
	v_mfma_f32_16x16x32_bf16 v[44:47], v[174:177], v[228:231], v[44:47]
	v_mfma_f32_16x16x32_bf16 v[32:35], v[144:147], v[232:235], v[32:35]
	v_mfma_f32_16x16x32_bf16 v[32:35], v[166:169], v[236:239], v[32:35]
	v_mfma_f32_16x16x32_bf16 v[28:31], v[170:173], v[232:235], v[28:31]
	v_mfma_f32_16x16x32_bf16 v[28:31], v[174:177], v[236:239], v[28:31]
	v_mfma_f32_16x16x32_bf16 v[16:19], v[144:147], v[240:243], v[16:19]
	v_mfma_f32_16x16x32_bf16 v[16:19], v[166:169], v[244:247], v[16:19]
	v_mfma_f32_16x16x32_bf16 v[12:15], v[170:173], v[240:243], v[12:15]
	v_mfma_f32_16x16x32_bf16 v[12:15], v[174:177], v[244:247], v[12:15]
	s_setprio 0
	s_setprio 1
	v_mfma_f32_16x16x32_bf16 v[56:59], v[178:181], v[194:197], v[56:59]
	v_mfma_f32_16x16x32_bf16 v[56:59], v[182:185], v[198:201], v[56:59]
	v_mfma_f32_16x16x32_bf16 v[52:55], v[186:189], v[194:197], v[52:55]
	v_mfma_f32_16x16x32_bf16 v[52:55], v[190:193], v[198:201], v[52:55]
	v_mfma_f32_16x16x32_bf16 v[40:43], v[178:181], v[202:205], v[40:43]
	v_mfma_f32_16x16x32_bf16 v[40:43], v[182:185], v[228:231], v[40:43]
	v_mfma_f32_16x16x32_bf16 v[36:39], v[186:189], v[202:205], v[36:39]
	v_mfma_f32_16x16x32_bf16 v[36:39], v[190:193], v[228:231], v[36:39]
	v_mfma_f32_16x16x32_bf16 v[24:27], v[178:181], v[232:235], v[24:27]
	v_mfma_f32_16x16x32_bf16 v[24:27], v[182:185], v[236:239], v[24:27]
	v_mfma_f32_16x16x32_bf16 v[20:23], v[186:189], v[232:235], v[20:23]
	v_mfma_f32_16x16x32_bf16 v[20:23], v[190:193], v[236:239], v[20:23]
	s_setprio 2
	s_barrier
	v_mfma_f32_16x16x32_bf16 v[6:9], v[178:181], v[240:243], v[6:9]
	v_mfma_f32_16x16x32_bf16 v[6:9], v[182:185], v[244:247], v[6:9]
	v_mfma_f32_16x16x32_bf16 v[2:5], v[186:189], v[240:243], v[2:5]
	v_mfma_f32_16x16x32_bf16 v[2:5], v[190:193], v[244:247], v[2:5]
	s_setprio 0
	s_add_i32 s2, 0, 0x18000
	s_add_i32 s3, 0, 0x1c000
	v_add_u32_e32 v174, s2, v10
	v_add_u32_e32 v190, s3, v10
	ds_read_b128 v[144:147], v174
	ds_read_b128 v[166:169], v174 offset:1024
	ds_read_b128 v[170:173], v174 offset:2048
	ds_read_b128 v[174:177], v174 offset:3072
	ds_read_b128 v[178:181], v190
	ds_read_b128 v[182:185], v190 offset:1024
	ds_read_b128 v[186:189], v190 offset:2048
	ds_read_b128 v[190:193], v190 offset:3072
	s_add_u32 s0, s10, 0x160000
	s_addc_u32 s1, s11, 0
	s_mov_b32 m0, s19
	v_lshl_add_u64 v[218:219], s[0:1], 0, v[138:139]
	ds_read_b128 v[194:197], v161 offset:32768
	ds_read_b128 v[198:201], v161 offset:33792
	ds_read_b128 v[202:205], v161 offset:34816
	ds_read_b128 v[228:231], v161 offset:35840
	ds_read_b128 v[232:235], v161 offset:36864
	ds_read_b128 v[236:239], v161 offset:37888
	ds_read_b128 v[240:243], v161 offset:38912
	ds_read_b128 v[244:247], v161 offset:39936
	global_load_lds_dwordx4 v[218:219], off
	v_lshl_add_u64 v[218:219], s[0:1], 0, v[134:135]
	s_mov_b32 m0, s22
	s_nop 0
	global_load_lds_dwordx4 v[218:219], off
	s_waitcnt vmcnt(8)
	s_waitcnt lgkmcnt(0)
	s_barrier
	s_setprio 1
	s_waitcnt lgkmcnt(0)
	v_mfma_f32_16x16x32_bf16 v[128:131], v[144:147], v[194:197], v[128:131]
	v_mfma_f32_16x16x32_bf16 v[128:131], v[166:169], v[198:201], v[128:131]
	v_mfma_f32_16x16x32_bf16 v[124:127], v[170:173], v[194:197], v[124:127]
	v_mfma_f32_16x16x32_bf16 v[124:127], v[174:177], v[198:201], v[124:127]
	v_mfma_f32_16x16x32_bf16 v[112:115], v[144:147], v[202:205], v[112:115]
	v_mfma_f32_16x16x32_bf16 v[112:115], v[166:169], v[228:231], v[112:115]
	v_mfma_f32_16x16x32_bf16 v[108:111], v[170:173], v[202:205], v[108:111]
	v_mfma_f32_16x16x32_bf16 v[108:111], v[174:177], v[228:231], v[108:111]
	v_mfma_f32_16x16x32_bf16 v[96:99], v[144:147], v[232:235], v[96:99]
	v_mfma_f32_16x16x32_bf16 v[96:99], v[166:169], v[236:239], v[96:99]
	v_mfma_f32_16x16x32_bf16 v[92:95], v[170:173], v[232:235], v[92:95]
	v_mfma_f32_16x16x32_bf16 v[92:95], v[174:177], v[236:239], v[92:95]
	v_mfma_f32_16x16x32_bf16 v[80:83], v[144:147], v[240:243], v[80:83]
	v_mfma_f32_16x16x32_bf16 v[80:83], v[166:169], v[244:247], v[80:83]
	v_mfma_f32_16x16x32_bf16 v[76:79], v[170:173], v[240:243], v[76:79]
	v_mfma_f32_16x16x32_bf16 v[76:79], v[174:177], v[244:247], v[76:79]
	s_setprio 0
	s_setprio 1
	v_mfma_f32_16x16x32_bf16 v[120:123], v[178:181], v[194:197], v[120:123]
	v_mfma_f32_16x16x32_bf16 v[120:123], v[182:185], v[198:201], v[120:123]
	v_mfma_f32_16x16x32_bf16 v[116:119], v[186:189], v[194:197], v[116:119]
	v_mfma_f32_16x16x32_bf16 v[116:119], v[190:193], v[198:201], v[116:119]
	v_mfma_f32_16x16x32_bf16 v[104:107], v[178:181], v[202:205], v[104:107]
	v_mfma_f32_16x16x32_bf16 v[104:107], v[182:185], v[228:231], v[104:107]
	v_mfma_f32_16x16x32_bf16 v[100:103], v[186:189], v[202:205], v[100:103]
	v_mfma_f32_16x16x32_bf16 v[100:103], v[190:193], v[228:231], v[100:103]
	v_mfma_f32_16x16x32_bf16 v[88:91], v[178:181], v[232:235], v[88:91]
	v_mfma_f32_16x16x32_bf16 v[88:91], v[182:185], v[236:239], v[88:91]
	v_mfma_f32_16x16x32_bf16 v[84:87], v[186:189], v[232:235], v[84:87]
	v_mfma_f32_16x16x32_bf16 v[84:87], v[190:193], v[236:239], v[84:87]
	s_setprio 2
	s_barrier
	v_mfma_f32_16x16x32_bf16 v[72:75], v[178:181], v[240:243], v[72:75]
	v_mfma_f32_16x16x32_bf16 v[72:75], v[182:185], v[244:247], v[72:75]
	v_mfma_f32_16x16x32_bf16 v[68:71], v[186:189], v[240:243], v[68:71]
	v_mfma_f32_16x16x32_bf16 v[68:71], v[190:193], v[244:247], v[68:71]
	s_setprio 0
	s_add_i32 s0, s2, s14
	v_lshl_add_u64 v[148:149], v[148:149], 0, s[86:87]
	s_mov_b32 m0, s0
	ds_read_b128 v[194:197], v161 offset:49152
	ds_read_b128 v[198:201], v161 offset:50176
	ds_read_b128 v[202:205], v161 offset:51200
	ds_read_b128 v[228:231], v161 offset:52224
	ds_read_b128 v[232:235], v161 offset:53248
	ds_read_b128 v[236:239], v161 offset:54272
	ds_read_b128 v[240:243], v161 offset:55296
	ds_read_b128 v[244:247], v161 offset:56320
	global_load_lds_dwordx4 v[148:149], off
	s_add_i32 m0, s0, 0x2000
	s_add_u32 s0, s8, 0x160080
	v_lshl_add_u64 v[148:149], v[212:213], 0, s[86:87]
	s_addc_u32 s1, s9, 0
	s_add_i32 s2, s3, s14
	global_load_lds_dwordx4 v[148:149], off
	v_lshl_add_u64 v[148:149], s[0:1], 0, v[136:137]
	s_mov_b32 m0, s2
	s_nop 0
	global_load_lds_dwordx4 v[148:149], off
	v_lshl_add_u64 v[148:149], s[0:1], 0, v[132:133]
	s_add_i32 m0, s2, 0x2000
	s_nop 0
	global_load_lds_dwordx4 v[148:149], off
	v_lshl_add_u64 v[148:149], v[214:215], 0, s[86:87]
	s_mov_b32 m0, s31
	s_nop 0
	global_load_lds_dwordx4 v[148:149], off
	v_lshl_add_u64 v[148:149], v[216:217], 0, s[86:87]
	s_mov_b32 m0, s34
	s_nop 0
	global_load_lds_dwordx4 v[148:149], off
	s_waitcnt vmcnt(8)
	s_waitcnt lgkmcnt(0)
	s_barrier
	s_setprio 1
	s_waitcnt lgkmcnt(0)
	v_mfma_f32_16x16x32_bf16 v[64:67], v[144:147], v[194:197], v[64:67]
	v_mfma_f32_16x16x32_bf16 v[64:67], v[166:169], v[198:201], v[64:67]
	v_mfma_f32_16x16x32_bf16 v[60:63], v[170:173], v[194:197], v[60:63]
	v_mfma_f32_16x16x32_bf16 v[60:63], v[174:177], v[198:201], v[60:63]
	v_mfma_f32_16x16x32_bf16 v[48:51], v[144:147], v[202:205], v[48:51]
	v_mfma_f32_16x16x32_bf16 v[48:51], v[166:169], v[228:231], v[48:51]
	v_mfma_f32_16x16x32_bf16 v[44:47], v[170:173], v[202:205], v[44:47]
	v_mfma_f32_16x16x32_bf16 v[44:47], v[174:177], v[228:231], v[44:47]
	v_mfma_f32_16x16x32_bf16 v[32:35], v[144:147], v[232:235], v[32:35]
	v_mfma_f32_16x16x32_bf16 v[32:35], v[166:169], v[236:239], v[32:35]
	v_mfma_f32_16x16x32_bf16 v[28:31], v[170:173], v[232:235], v[28:31]
	v_mfma_f32_16x16x32_bf16 v[28:31], v[174:177], v[236:239], v[28:31]
	v_mfma_f32_16x16x32_bf16 v[16:19], v[144:147], v[240:243], v[16:19]
	v_mfma_f32_16x16x32_bf16 v[16:19], v[166:169], v[244:247], v[16:19]
	v_mfma_f32_16x16x32_bf16 v[12:15], v[170:173], v[240:243], v[12:15]
	v_mfma_f32_16x16x32_bf16 v[12:15], v[174:177], v[244:247], v[12:15]
	s_setprio 0
	s_setprio 1
	v_mfma_f32_16x16x32_bf16 v[56:59], v[178:181], v[194:197], v[56:59]
	v_mfma_f32_16x16x32_bf16 v[56:59], v[182:185], v[198:201], v[56:59]
	v_mfma_f32_16x16x32_bf16 v[52:55], v[186:189], v[194:197], v[52:55]
	v_mfma_f32_16x16x32_bf16 v[52:55], v[190:193], v[198:201], v[52:55]
	v_mfma_f32_16x16x32_bf16 v[40:43], v[178:181], v[202:205], v[40:43]
	v_mfma_f32_16x16x32_bf16 v[40:43], v[182:185], v[228:231], v[40:43]
	v_mfma_f32_16x16x32_bf16 v[36:39], v[186:189], v[202:205], v[36:39]
	v_mfma_f32_16x16x32_bf16 v[36:39], v[190:193], v[228:231], v[36:39]
	v_mfma_f32_16x16x32_bf16 v[24:27], v[178:181], v[232:235], v[24:27]
	v_mfma_f32_16x16x32_bf16 v[24:27], v[182:185], v[236:239], v[24:27]
	v_mfma_f32_16x16x32_bf16 v[20:23], v[186:189], v[232:235], v[20:23]
	v_mfma_f32_16x16x32_bf16 v[20:23], v[190:193], v[236:239], v[20:23]
	s_setprio 2
	s_barrier
	v_mfma_f32_16x16x32_bf16 v[6:9], v[178:181], v[240:243], v[6:9]
	v_mfma_f32_16x16x32_bf16 v[6:9], v[182:185], v[244:247], v[6:9]
	v_mfma_f32_16x16x32_bf16 v[2:5], v[186:189], v[240:243], v[2:5]
	v_mfma_f32_16x16x32_bf16 v[2:5], v[190:193], v[244:247], v[2:5]
	s_setprio 0
	s_add_i32 s49, s49, 2
	s_add_u32 s33, s33, 0x100
	s_addc_u32 s48, s48, 0
	s_cmpk_gt_u32 s49, 0x55
	s_mov_b64 s[0:1], s[4:5]
	s_cbranch_scc0 .LBB0_986
	s_and_b64 vcc, exec, s[42:43]
	s_cbranch_vccz .LBB0_989
	s_barrier

.LBB0_1077:
	s_add_u32 s2, s30, 0xfff80080
	s_addc_u32 s3, s31, -1
	s_add_i32 s6, 0, 0x10000
	s_cmp_eq_u32 s61, 28
	s_cselect_b32 s41, s11, s3
	s_cselect_b32 s40, s19, s2
	v_add_u32_e32 v148, s6, v10
	s_cselect_b32 s35, s9, s60
	s_cselect_b32 s34, s29, s59
	s_add_i32 s7, 0, 0x14000
	ds_read_b128 v[166:169], v148
	ds_read_b128 v[170:173], v148 offset:1024
	ds_read_b128 v[174:177], v148 offset:2048
	ds_read_b128 v[178:181], v148 offset:3072
	v_add_u32_e32 v148, s7, v10
	ds_read_b128 v[182:185], v148
	ds_read_b128 v[186:189], v148 offset:1024
	ds_read_b128 v[190:193], v148 offset:2048
	ds_read_b128 v[194:197], v148 offset:3072
	v_lshl_add_u64 v[148:149], s[30:31], 0, v[144:145]
	s_add_i32 m0, s48, 0xc000
	ds_read_b128 v[198:201], v161
	ds_read_b128 v[202:205], v161 offset:1024
	ds_read_b128 v[228:231], v161 offset:2048
	ds_read_b128 v[232:235], v161 offset:3072
	ds_read_b128 v[236:239], v161 offset:4096
	ds_read_b128 v[240:243], v161 offset:5120
	ds_read_b128 v[244:247], v161 offset:6144
	ds_read_b128 v[212:215], v161 offset:7168
	global_load_lds_dwordx4 v[148:149], off
	v_lshl_add_u64 v[148:149], s[30:31], 0, v[146:147]
	s_add_i32 m0, s48, 0xe000
	s_nop 0
	global_load_lds_dwordx4 v[148:149], off
	s_waitcnt vmcnt(8)
	s_waitcnt lgkmcnt(0)
	s_barrier
	s_setprio 1
	s_waitcnt lgkmcnt(0)
	v_mfma_f32_16x16x32_bf16 v[128:131], v[166:169], v[198:201], v[128:131]
	v_mfma_f32_16x16x32_bf16 v[128:131], v[170:173], v[202:205], v[128:131]
	v_mfma_f32_16x16x32_bf16 v[124:127], v[174:177], v[198:201], v[124:127]
	v_mfma_f32_16x16x32_bf16 v[124:127], v[178:181], v[202:205], v[124:127]
	v_mfma_f32_16x16x32_bf16 v[112:115], v[166:169], v[228:231], v[112:115]
	v_mfma_f32_16x16x32_bf16 v[112:115], v[170:173], v[232:235], v[112:115]
	v_mfma_f32_16x16x32_bf16 v[108:111], v[174:177], v[228:231], v[108:111]
	v_mfma_f32_16x16x32_bf16 v[108:111], v[178:181], v[232:235], v[108:111]
	v_mfma_f32_16x16x32_bf16 v[96:99], v[166:169], v[236:239], v[96:99]
	v_mfma_f32_16x16x32_bf16 v[96:99], v[170:173], v[240:243], v[96:99]
	v_mfma_f32_16x16x32_bf16 v[92:95], v[174:177], v[236:239], v[92:95]
	v_mfma_f32_16x16x32_bf16 v[92:95], v[178:181], v[240:243], v[92:95]
	v_mfma_f32_16x16x32_bf16 v[80:83], v[166:169], v[244:247], v[80:83]
	v_mfma_f32_16x16x32_bf16 v[80:83], v[170:173], v[212:215], v[80:83]
	v_mfma_f32_16x16x32_bf16 v[76:79], v[174:177], v[244:247], v[76:79]
	v_mfma_f32_16x16x32_bf16 v[76:79], v[178:181], v[212:215], v[76:79]
	s_setprio 0
	s_setprio 1
	v_mfma_f32_16x16x32_bf16 v[120:123], v[182:185], v[198:201], v[120:123]
	v_mfma_f32_16x16x32_bf16 v[120:123], v[186:189], v[202:205], v[120:123]
	v_mfma_f32_16x16x32_bf16 v[116:119], v[190:193], v[198:201], v[116:119]
	v_mfma_f32_16x16x32_bf16 v[116:119], v[194:197], v[202:205], v[116:119]
	v_mfma_f32_16x16x32_bf16 v[104:107], v[182:185], v[228:231], v[104:107]
	v_mfma_f32_16x16x32_bf16 v[104:107], v[186:189], v[232:235], v[104:107]
	v_mfma_f32_16x16x32_bf16 v[100:103], v[190:193], v[228:231], v[100:103]
	v_mfma_f32_16x16x32_bf16 v[100:103], v[194:197], v[232:235], v[100:103]
	v_mfma_f32_16x16x32_bf16 v[88:91], v[182:185], v[236:239], v[88:91]
	v_mfma_f32_16x16x32_bf16 v[88:91], v[186:189], v[240:243], v[88:91]
	v_mfma_f32_16x16x32_bf16 v[84:87], v[190:193], v[236:239], v[84:87]
	v_mfma_f32_16x16x32_bf16 v[84:87], v[194:197], v[240:243], v[84:87]
	s_setprio 2
	s_barrier
	v_mfma_f32_16x16x32_bf16 v[72:75], v[182:185], v[244:247], v[72:75]
	v_mfma_f32_16x16x32_bf16 v[72:75], v[186:189], v[212:215], v[72:75]
	v_mfma_f32_16x16x32_bf16 v[68:71], v[190:193], v[244:247], v[68:71]
	v_mfma_f32_16x16x32_bf16 v[68:71], v[194:197], v[212:215], v[68:71]
	s_setprio 0
	s_add_i32 s2, s6, s47
	v_lshl_add_u64 v[148:149], s[34:35], 0, v[134:135]
	s_mov_b32 m0, s2
	ds_read_b128 v[198:201], v161 offset:16384
	ds_read_b128 v[202:205], v161 offset:17408
	ds_read_b128 v[212:215], v161 offset:18432
	ds_read_b128 v[228:231], v161 offset:19456
	ds_read_b128 v[232:235], v161 offset:20480
	ds_read_b128 v[236:239], v161 offset:21504
	ds_read_b128 v[240:243], v161 offset:22528
	ds_read_b128 v[244:247], v161 offset:23552
	global_load_lds_dwordx4 v[148:149], off
	s_add_i32 m0, s2, 0x2000
	s_add_u32 s2, s34, 0x80000
	v_lshl_add_u64 v[216:217], s[34:35], 0, v[138:139]
	s_addc_u32 s3, s35, 0
	s_add_i32 s6, s7, s47
	global_load_lds_dwordx4 v[216:217], off
	v_lshl_add_u64 v[218:219], s[2:3], 0, v[134:135]
	s_mov_b32 m0, s6
	v_lshl_add_u64 v[248:249], s[40:41], 0, v[136:137]
	global_load_lds_dwordx4 v[218:219], off
	v_lshl_add_u64 v[218:219], s[2:3], 0, v[138:139]
	s_add_i32 m0, s6, 0x2000
	s_nop 0
	global_load_lds_dwordx4 v[218:219], off
	v_lshl_add_u64 v[218:219], s[40:41], 0, v[132:133]
	s_mov_b32 m0, s48
	s_nop 0
	global_load_lds_dwordx4 v[218:219], off
	s_mov_b32 m0, s49
	s_nop 0
	global_load_lds_dwordx4 v[248:249], off
	s_waitcnt vmcnt(8)
	s_waitcnt lgkmcnt(0)
	s_barrier
	s_setprio 1
	s_waitcnt lgkmcnt(0)
	v_mfma_f32_16x16x32_bf16 v[64:67], v[166:169], v[198:201], v[64:67]
	v_mfma_f32_16x16x32_bf16 v[64:67], v[170:173], v[202:205], v[64:67]
	v_mfma_f32_16x16x32_bf16 v[60:63], v[174:177], v[198:201], v[60:63]
	v_mfma_f32_16x16x32_bf16 v[60:63], v[178:181], v[202:205], v[60:63]
	v_mfma_f32_16x16x32_bf16 v[48:51], v[166:169], v[212:215], v[48:51]
	v_mfma_f32_16x16x32_bf16 v[48:51], v[170:173], v[228:231], v[48:51]
	v_mfma_f32_16x16x32_bf16 v[44:47], v[174:177], v[212:215], v[44:47]
	v_mfma_f32_16x16x32_bf16 v[44:47], v[178:181], v[228:231], v[44:47]
	v_mfma_f32_16x16x32_bf16 v[32:35], v[166:169], v[232:235], v[32:35]
	v_mfma_f32_16x16x32_bf16 v[32:35], v[170:173], v[236:239], v[32:35]
	v_mfma_f32_16x16x32_bf16 v[28:31], v[174:177], v[232:235], v[28:31]
	v_mfma_f32_16x16x32_bf16 v[28:31], v[178:181], v[236:239], v[28:31]
	v_mfma_f32_16x16x32_bf16 v[16:19], v[166:169], v[240:243], v[16:19]
	v_mfma_f32_16x16x32_bf16 v[16:19], v[170:173], v[244:247], v[16:19]
	v_mfma_f32_16x16x32_bf16 v[12:15], v[174:177], v[240:243], v[12:15]
	v_mfma_f32_16x16x32_bf16 v[12:15], v[178:181], v[244:247], v[12:15]
	s_setprio 0
	s_setprio 1
	v_mfma_f32_16x16x32_bf16 v[56:59], v[182:185], v[198:201], v[56:59]
	v_mfma_f32_16x16x32_bf16 v[56:59], v[186:189], v[202:205], v[56:59]
	v_mfma_f32_16x16x32_bf16 v[52:55], v[190:193], v[198:201], v[52:55]
	v_mfma_f32_16x16x32_bf16 v[52:55], v[194:197], v[202:205], v[52:55]
	v_mfma_f32_16x16x32_bf16 v[40:43], v[182:185], v[212:215], v[40:43]
	v_mfma_f32_16x16x32_bf16 v[40:43], v[186:189], v[228:231], v[40:43]
	v_mfma_f32_16x16x32_bf16 v[36:39], v[190:193], v[212:215], v[36:39]
	v_mfma_f32_16x16x32_bf16 v[36:39], v[194:197], v[228:231], v[36:39]
	v_mfma_f32_16x16x32_bf16 v[24:27], v[182:185], v[232:235], v[24:27]
	v_mfma_f32_16x16x32_bf16 v[24:27], v[186:189], v[236:239], v[24:27]
	v_mfma_f32_16x16x32_bf16 v[20:23], v[190:193], v[232:235], v[20:23]
	v_mfma_f32_16x16x32_bf16 v[20:23], v[194:197], v[236:239], v[20:23]
	s_setprio 2
	s_barrier
	v_mfma_f32_16x16x32_bf16 v[6:9], v[182:185], v[240:243], v[6:9]
	v_mfma_f32_16x16x32_bf16 v[6:9], v[186:189], v[244:247], v[6:9]
	v_mfma_f32_16x16x32_bf16 v[2:5], v[190:193], v[240:243], v[2:5]
	v_mfma_f32_16x16x32_bf16 v[2:5], v[194:197], v[244:247], v[2:5]
	s_setprio 0
	s_add_i32 s6, 0, 0x18000
	s_add_i32 s7, 0, 0x1c000
	v_add_u32_e32 v178, s6, v10
	v_add_u32_e32 v194, s7, v10
	ds_read_b128 v[166:169], v178
	ds_read_b128 v[170:173], v178 offset:1024
	ds_read_b128 v[174:177], v178 offset:2048
	ds_read_b128 v[178:181], v178 offset:3072
	ds_read_b128 v[182:185], v194
	ds_read_b128 v[186:189], v194 offset:1024
	ds_read_b128 v[190:193], v194 offset:2048
	ds_read_b128 v[194:197], v194 offset:3072
	s_add_u32 s2, s40, 0x80000
	s_addc_u32 s3, s41, 0
	s_mov_b32 m0, s50
	v_lshl_add_u64 v[220:221], s[2:3], 0, v[132:133]
	ds_read_b128 v[198:201], v161 offset:32768
	ds_read_b128 v[202:205], v161 offset:33792
	ds_read_b128 v[212:215], v161 offset:34816
	ds_read_b128 v[228:231], v161 offset:35840
	ds_read_b128 v[232:235], v161 offset:36864
	ds_read_b128 v[236:239], v161 offset:37888
	ds_read_b128 v[240:243], v161 offset:38912
	ds_read_b128 v[244:247], v161 offset:39936
	global_load_lds_dwordx4 v[220:221], off
	v_lshl_add_u64 v[220:221], s[2:3], 0, v[136:137]
	s_mov_b32 m0, s51
	s_nop 0
	global_load_lds_dwordx4 v[220:221], off
	s_waitcnt vmcnt(8)
	s_waitcnt lgkmcnt(0)
	s_barrier
	s_setprio 1
	s_waitcnt lgkmcnt(0)
	v_mfma_f32_16x16x32_bf16 v[128:131], v[166:169], v[198:201], v[128:131]
	v_mfma_f32_16x16x32_bf16 v[128:131], v[170:173], v[202:205], v[128:131]
	v_mfma_f32_16x16x32_bf16 v[124:127], v[174:177], v[198:201], v[124:127]
	v_mfma_f32_16x16x32_bf16 v[124:127], v[178:181], v[202:205], v[124:127]
	v_mfma_f32_16x16x32_bf16 v[112:115], v[166:169], v[212:215], v[112:115]
	v_mfma_f32_16x16x32_bf16 v[112:115], v[170:173], v[228:231], v[112:115]
	v_mfma_f32_16x16x32_bf16 v[108:111], v[174:177], v[212:215], v[108:111]
	v_mfma_f32_16x16x32_bf16 v[108:111], v[178:181], v[228:231], v[108:111]
	v_mfma_f32_16x16x32_bf16 v[96:99], v[166:169], v[232:235], v[96:99]
	v_mfma_f32_16x16x32_bf16 v[96:99], v[170:173], v[236:239], v[96:99]
	v_mfma_f32_16x16x32_bf16 v[92:95], v[174:177], v[232:235], v[92:95]
	v_mfma_f32_16x16x32_bf16 v[92:95], v[178:181], v[236:239], v[92:95]
	v_mfma_f32_16x16x32_bf16 v[80:83], v[166:169], v[240:243], v[80:83]
	v_mfma_f32_16x16x32_bf16 v[80:83], v[170:173], v[244:247], v[80:83]
	v_mfma_f32_16x16x32_bf16 v[76:79], v[174:177], v[240:243], v[76:79]
	v_mfma_f32_16x16x32_bf16 v[76:79], v[178:181], v[244:247], v[76:79]
	s_setprio 0
	s_setprio 1
	v_mfma_f32_16x16x32_bf16 v[120:123], v[182:185], v[198:201], v[120:123]
	v_mfma_f32_16x16x32_bf16 v[120:123], v[186:189], v[202:205], v[120:123]
	v_mfma_f32_16x16x32_bf16 v[116:119], v[190:193], v[198:201], v[116:119]
	v_mfma_f32_16x16x32_bf16 v[116:119], v[194:197], v[202:205], v[116:119]
	v_mfma_f32_16x16x32_bf16 v[104:107], v[182:185], v[212:215], v[104:107]
	v_mfma_f32_16x16x32_bf16 v[104:107], v[186:189], v[228:231], v[104:107]
	v_mfma_f32_16x16x32_bf16 v[100:103], v[190:193], v[212:215], v[100:103]
	v_mfma_f32_16x16x32_bf16 v[100:103], v[194:197], v[228:231], v[100:103]
	v_mfma_f32_16x16x32_bf16 v[88:91], v[182:185], v[232:235], v[88:91]
	v_mfma_f32_16x16x32_bf16 v[88:91], v[186:189], v[236:239], v[88:91]
	v_mfma_f32_16x16x32_bf16 v[84:87], v[190:193], v[232:235], v[84:87]
	v_mfma_f32_16x16x32_bf16 v[84:87], v[194:197], v[236:239], v[84:87]
	s_setprio 2
	s_barrier
	v_mfma_f32_16x16x32_bf16 v[72:75], v[182:185], v[240:243], v[72:75]
	v_mfma_f32_16x16x32_bf16 v[72:75], v[186:189], v[244:247], v[72:75]
	v_mfma_f32_16x16x32_bf16 v[68:71], v[190:193], v[240:243], v[68:71]
	v_mfma_f32_16x16x32_bf16 v[68:71], v[194:197], v[244:247], v[68:71]
	s_setprio 0
	s_add_i32 s2, s6, s47
	v_lshl_add_u64 v[148:149], v[148:149], 0, s[86:87]
	s_mov_b32 m0, s2
	ds_read_b128 v[198:201], v161 offset:49152
	ds_read_b128 v[202:205], v161 offset:50176
	ds_read_b128 v[212:215], v161 offset:51200
	ds_read_b128 v[228:231], v161 offset:52224
	ds_read_b128 v[232:235], v161 offset:53248
	ds_read_b128 v[236:239], v161 offset:54272
	ds_read_b128 v[240:243], v161 offset:55296
	ds_read_b128 v[244:247], v161 offset:56320
	global_load_lds_dwordx4 v[148:149], off
	s_add_i32 m0, s2, 0x2000
	s_add_u32 s2, s34, 0x80080
	v_lshl_add_u64 v[148:149], v[216:217], 0, s[86:87]
	s_addc_u32 s3, s35, 0
	s_add_i32 s6, s7, s47
	global_load_lds_dwordx4 v[148:149], off
	v_lshl_add_u64 v[148:149], s[2:3], 0, v[134:135]
	s_mov_b32 m0, s6
	s_nop 0
	global_load_lds_dwordx4 v[148:149], off
	v_lshl_add_u64 v[148:149], s[2:3], 0, v[138:139]
	s_add_i32 m0, s6, 0x2000
	s_nop 0
	global_load_lds_dwordx4 v[148:149], off
	v_lshl_add_u64 v[148:149], v[218:219], 0, s[86:87]
	s_mov_b32 m0, s53
	s_nop 0
	global_load_lds_dwordx4 v[148:149], off
	v_lshl_add_u64 v[148:149], v[248:249], 0, s[86:87]
	s_mov_b32 m0, s54
	s_nop 0
	global_load_lds_dwordx4 v[148:149], off
	s_waitcnt vmcnt(8)
	s_waitcnt lgkmcnt(0)
	s_barrier
	s_setprio 1
	s_waitcnt lgkmcnt(0)
	v_mfma_f32_16x16x32_bf16 v[64:67], v[166:169], v[198:201], v[64:67]
	v_mfma_f32_16x16x32_bf16 v[64:67], v[170:173], v[202:205], v[64:67]
	v_mfma_f32_16x16x32_bf16 v[60:63], v[174:177], v[198:201], v[60:63]
	v_mfma_f32_16x16x32_bf16 v[60:63], v[178:181], v[202:205], v[60:63]
	v_mfma_f32_16x16x32_bf16 v[48:51], v[166:169], v[212:215], v[48:51]
	v_mfma_f32_16x16x32_bf16 v[48:51], v[170:173], v[228:231], v[48:51]
	v_mfma_f32_16x16x32_bf16 v[44:47], v[174:177], v[212:215], v[44:47]
	v_mfma_f32_16x16x32_bf16 v[44:47], v[178:181], v[228:231], v[44:47]
	v_mfma_f32_16x16x32_bf16 v[32:35], v[166:169], v[232:235], v[32:35]
	v_mfma_f32_16x16x32_bf16 v[32:35], v[170:173], v[236:239], v[32:35]
	v_mfma_f32_16x16x32_bf16 v[28:31], v[174:177], v[232:235], v[28:31]
	v_mfma_f32_16x16x32_bf16 v[28:31], v[178:181], v[236:239], v[28:31]
	v_mfma_f32_16x16x32_bf16 v[16:19], v[166:169], v[240:243], v[16:19]
	v_mfma_f32_16x16x32_bf16 v[16:19], v[170:173], v[244:247], v[16:19]
	v_mfma_f32_16x16x32_bf16 v[12:15], v[174:177], v[240:243], v[12:15]
	v_mfma_f32_16x16x32_bf16 v[12:15], v[178:181], v[244:247], v[12:15]
	s_setprio 0
	s_setprio 1
	v_mfma_f32_16x16x32_bf16 v[56:59], v[182:185], v[198:201], v[56:59]
	v_mfma_f32_16x16x32_bf16 v[56:59], v[186:189], v[202:205], v[56:59]
	v_mfma_f32_16x16x32_bf16 v[52:55], v[190:193], v[198:201], v[52:55]
	v_mfma_f32_16x16x32_bf16 v[52:55], v[194:197], v[202:205], v[52:55]
	v_mfma_f32_16x16x32_bf16 v[40:43], v[182:185], v[212:215], v[40:43]
	v_mfma_f32_16x16x32_bf16 v[40:43], v[186:189], v[228:231], v[40:43]
	v_mfma_f32_16x16x32_bf16 v[36:39], v[190:193], v[212:215], v[36:39]
	v_mfma_f32_16x16x32_bf16 v[36:39], v[194:197], v[228:231], v[36:39]
	v_mfma_f32_16x16x32_bf16 v[24:27], v[182:185], v[232:235], v[24:27]
	v_mfma_f32_16x16x32_bf16 v[24:27], v[186:189], v[236:239], v[24:27]
	v_mfma_f32_16x16x32_bf16 v[20:23], v[190:193], v[232:235], v[20:23]
	v_mfma_f32_16x16x32_bf16 v[20:23], v[194:197], v[236:239], v[20:23]
	s_setprio 2
	s_barrier
	v_mfma_f32_16x16x32_bf16 v[6:9], v[182:185], v[240:243], v[6:9]
	v_mfma_f32_16x16x32_bf16 v[6:9], v[186:189], v[244:247], v[6:9]
	v_mfma_f32_16x16x32_bf16 v[2:5], v[190:193], v[240:243], v[2:5]
	v_mfma_f32_16x16x32_bf16 v[2:5], v[194:197], v[244:247], v[2:5]
	s_setprio 0
	s_add_i32 s61, s61, 2
	s_add_u32 s30, s30, 0x100
	s_addc_u32 s31, s31, 0
	s_add_u32 s59, s59, 0x100
	s_addc_u32 s60, s60, 0
	s_cmp_gt_u32 s61, 29
	s_cbranch_scc0 .LBB0_1077
	s_and_b64 vcc, exec, s[4:5]
	s_cbranch_vccz .LBB0_1080
	s_barrier

.LBB0_2857:
	s_add_i32 s58, s2, 2
	s_add_u32 s3, s0, 0x80
	s_addc_u32 s4, s1, 0
	s_add_i32 s6, 0, 0x10000
	s_cmp_eq_u32 s55, s2
	s_cselect_b32 s5, s8, s4
	s_cselect_b32 s4, s9, s3
	v_add_u32_e32 v148, s6, v10
	s_cselect_b32 s3, s33, s49
	s_cselect_b32 s2, s41, s47
	s_add_i32 s7, 0, 0x14000
	ds_read_b128 v[144:147], v148
	ds_read_b128 v[166:169], v148 offset:1024
	ds_read_b128 v[170:173], v148 offset:2048
	ds_read_b128 v[174:177], v148 offset:3072
	v_add_u32_e32 v148, s7, v10
	ds_read_b128 v[178:181], v148
	ds_read_b128 v[182:185], v148 offset:1024
	ds_read_b128 v[186:189], v148 offset:2048
	ds_read_b128 v[190:193], v148 offset:3072
	v_lshl_add_u64 v[148:149], s[0:1], 0, v[140:141]
	s_add_i32 m0, s28, 0xc000
	ds_read_b128 v[194:197], v161
	ds_read_b128 v[198:201], v161 offset:1024
	ds_read_b128 v[202:205], v161 offset:2048
	ds_read_b128 v[212:215], v161 offset:3072
	ds_read_b128 v[228:231], v161 offset:4096
	ds_read_b128 v[232:235], v161 offset:5120
	ds_read_b128 v[236:239], v161 offset:6144
	ds_read_b128 v[240:243], v161 offset:7168
	global_load_lds_dwordx4 v[148:149], off
	v_lshl_add_u64 v[148:149], s[0:1], 0, v[142:143]
	s_add_i32 m0, s28, 0xe000
	s_nop 0
	global_load_lds_dwordx4 v[148:149], off
	s_waitcnt vmcnt(8)
	s_waitcnt lgkmcnt(0)
	s_barrier
	s_setprio 1
	s_waitcnt lgkmcnt(0)
	v_mfma_f32_16x16x32_bf16 v[128:131], v[144:147], v[194:197], v[128:131]
	v_mfma_f32_16x16x32_bf16 v[128:131], v[166:169], v[198:201], v[128:131]
	v_mfma_f32_16x16x32_bf16 v[124:127], v[170:173], v[194:197], v[124:127]
	v_mfma_f32_16x16x32_bf16 v[124:127], v[174:177], v[198:201], v[124:127]
	v_mfma_f32_16x16x32_bf16 v[112:115], v[144:147], v[202:205], v[112:115]
	v_mfma_f32_16x16x32_bf16 v[112:115], v[166:169], v[212:215], v[112:115]
	v_mfma_f32_16x16x32_bf16 v[108:111], v[170:173], v[202:205], v[108:111]
	v_mfma_f32_16x16x32_bf16 v[108:111], v[174:177], v[212:215], v[108:111]
	v_mfma_f32_16x16x32_bf16 v[96:99], v[144:147], v[228:231], v[96:99]
	v_mfma_f32_16x16x32_bf16 v[96:99], v[166:169], v[232:235], v[96:99]
	v_mfma_f32_16x16x32_bf16 v[92:95], v[170:173], v[228:231], v[92:95]
	v_mfma_f32_16x16x32_bf16 v[92:95], v[174:177], v[232:235], v[92:95]
	v_mfma_f32_16x16x32_bf16 v[80:83], v[144:147], v[236:239], v[80:83]
	v_mfma_f32_16x16x32_bf16 v[80:83], v[166:169], v[240:243], v[80:83]
	v_mfma_f32_16x16x32_bf16 v[76:79], v[170:173], v[236:239], v[76:79]
	v_mfma_f32_16x16x32_bf16 v[76:79], v[174:177], v[240:243], v[76:79]
	s_setprio 0
	s_setprio 1
	v_mfma_f32_16x16x32_bf16 v[120:123], v[178:181], v[194:197], v[120:123]
	v_mfma_f32_16x16x32_bf16 v[120:123], v[182:185], v[198:201], v[120:123]
	v_mfma_f32_16x16x32_bf16 v[116:119], v[186:189], v[194:197], v[116:119]
	v_mfma_f32_16x16x32_bf16 v[116:119], v[190:193], v[198:201], v[116:119]
	v_mfma_f32_16x16x32_bf16 v[104:107], v[178:181], v[202:205], v[104:107]
	v_mfma_f32_16x16x32_bf16 v[104:107], v[182:185], v[212:215], v[104:107]
	v_mfma_f32_16x16x32_bf16 v[100:103], v[186:189], v[202:205], v[100:103]
	v_mfma_f32_16x16x32_bf16 v[100:103], v[190:193], v[212:215], v[100:103]
	v_mfma_f32_16x16x32_bf16 v[88:91], v[178:181], v[228:231], v[88:91]
	v_mfma_f32_16x16x32_bf16 v[88:91], v[182:185], v[232:235], v[88:91]
	v_mfma_f32_16x16x32_bf16 v[84:87], v[186:189], v[228:231], v[84:87]
	v_mfma_f32_16x16x32_bf16 v[84:87], v[190:193], v[232:235], v[84:87]
	s_setprio 2
	s_barrier
	v_mfma_f32_16x16x32_bf16 v[72:75], v[178:181], v[236:239], v[72:75]
	v_mfma_f32_16x16x32_bf16 v[72:75], v[182:185], v[240:243], v[72:75]
	v_mfma_f32_16x16x32_bf16 v[68:71], v[186:189], v[236:239], v[68:71]
	v_mfma_f32_16x16x32_bf16 v[68:71], v[190:193], v[240:243], v[68:71]
	s_setprio 0
	s_add_i32 s6, s6, s22
	v_lshl_add_u64 v[148:149], s[2:3], 0, v[136:137]
	s_mov_b32 m0, s6
	ds_read_b128 v[194:197], v161 offset:16384
	ds_read_b128 v[198:201], v161 offset:17408
	ds_read_b128 v[202:205], v161 offset:18432
	ds_read_b128 v[212:215], v161 offset:19456
	ds_read_b128 v[228:231], v161 offset:20480
	ds_read_b128 v[232:235], v161 offset:21504
	ds_read_b128 v[236:239], v161 offset:22528
	ds_read_b128 v[240:243], v161 offset:23552
	global_load_lds_dwordx4 v[148:149], off
	s_add_i32 m0, s6, 0x2000
	v_lshl_add_u64 v[216:217], s[2:3], 0, v[132:133]
	s_add_u32 s2, s2, s40
	s_addc_u32 s3, s3, 0
	s_add_i32 s6, s7, s22
	global_load_lds_dwordx4 v[216:217], off
	v_lshl_add_u64 v[218:219], s[2:3], 0, v[136:137]
	s_mov_b32 m0, s6
	v_lshl_add_u64 v[220:221], s[2:3], 0, v[132:133]
	global_load_lds_dwordx4 v[218:219], off
	s_add_i32 m0, s6, 0x2000
	v_lshl_add_u64 v[244:245], s[4:5], 0, v[138:139]
	global_load_lds_dwordx4 v[220:221], off
	s_mov_b32 m0, s28
	v_lshl_add_u64 v[246:247], s[4:5], 0, v[134:135]
	global_load_lds_dwordx4 v[244:245], off
	s_mov_b32 m0, s29
	s_nop 0
	global_load_lds_dwordx4 v[246:247], off
	s_waitcnt vmcnt(8)
	s_waitcnt lgkmcnt(0)
	s_barrier
	s_setprio 1
	s_waitcnt lgkmcnt(0)
	v_mfma_f32_16x16x32_bf16 v[64:67], v[144:147], v[194:197], v[64:67]
	v_mfma_f32_16x16x32_bf16 v[64:67], v[166:169], v[198:201], v[64:67]
	v_mfma_f32_16x16x32_bf16 v[60:63], v[170:173], v[194:197], v[60:63]
	v_mfma_f32_16x16x32_bf16 v[60:63], v[174:177], v[198:201], v[60:63]
	v_mfma_f32_16x16x32_bf16 v[48:51], v[144:147], v[202:205], v[48:51]
	v_mfma_f32_16x16x32_bf16 v[48:51], v[166:169], v[212:215], v[48:51]
	v_mfma_f32_16x16x32_bf16 v[44:47], v[170:173], v[202:205], v[44:47]
	v_mfma_f32_16x16x32_bf16 v[44:47], v[174:177], v[212:215], v[44:47]
	v_mfma_f32_16x16x32_bf16 v[32:35], v[144:147], v[228:231], v[32:35]
	v_mfma_f32_16x16x32_bf16 v[32:35], v[166:169], v[232:235], v[32:35]
	v_mfma_f32_16x16x32_bf16 v[28:31], v[170:173], v[228:231], v[28:31]
	v_mfma_f32_16x16x32_bf16 v[28:31], v[174:177], v[232:235], v[28:31]
	v_mfma_f32_16x16x32_bf16 v[16:19], v[144:147], v[236:239], v[16:19]
	v_mfma_f32_16x16x32_bf16 v[16:19], v[166:169], v[240:243], v[16:19]
	v_mfma_f32_16x16x32_bf16 v[12:15], v[170:173], v[236:239], v[12:15]
	v_mfma_f32_16x16x32_bf16 v[12:15], v[174:177], v[240:243], v[12:15]
	s_setprio 0
	s_setprio 1
	v_mfma_f32_16x16x32_bf16 v[56:59], v[178:181], v[194:197], v[56:59]
	v_mfma_f32_16x16x32_bf16 v[56:59], v[182:185], v[198:201], v[56:59]
	v_mfma_f32_16x16x32_bf16 v[52:55], v[186:189], v[194:197], v[52:55]
	v_mfma_f32_16x16x32_bf16 v[52:55], v[190:193], v[198:201], v[52:55]
	v_mfma_f32_16x16x32_bf16 v[40:43], v[178:181], v[202:205], v[40:43]
	v_mfma_f32_16x16x32_bf16 v[40:43], v[182:185], v[212:215], v[40:43]
	v_mfma_f32_16x16x32_bf16 v[36:39], v[186:189], v[202:205], v[36:39]
	v_mfma_f32_16x16x32_bf16 v[36:39], v[190:193], v[212:215], v[36:39]
	v_mfma_f32_16x16x32_bf16 v[24:27], v[178:181], v[228:231], v[24:27]
	v_mfma_f32_16x16x32_bf16 v[24:27], v[182:185], v[232:235], v[24:27]
	v_mfma_f32_16x16x32_bf16 v[20:23], v[186:189], v[228:231], v[20:23]
	v_mfma_f32_16x16x32_bf16 v[20:23], v[190:193], v[232:235], v[20:23]
	s_setprio 2
	s_barrier
	v_mfma_f32_16x16x32_bf16 v[6:9], v[178:181], v[236:239], v[6:9]
	v_mfma_f32_16x16x32_bf16 v[6:9], v[182:185], v[240:243], v[6:9]
	v_mfma_f32_16x16x32_bf16 v[2:5], v[186:189], v[236:239], v[2:5]
	v_mfma_f32_16x16x32_bf16 v[2:5], v[190:193], v[240:243], v[2:5]
	s_setprio 0
	s_add_i32 s6, 0, 0x18000
	s_add_i32 s7, 0, 0x1c000
	v_add_u32_e32 v174, s6, v10
	v_add_u32_e32 v190, s7, v10
	ds_read_b128 v[144:147], v174
	ds_read_b128 v[166:169], v174 offset:1024
	ds_read_b128 v[170:173], v174 offset:2048
	ds_read_b128 v[174:177], v174 offset:3072
	ds_read_b128 v[178:181], v190
	ds_read_b128 v[182:185], v190 offset:1024
	ds_read_b128 v[186:189], v190 offset:2048
	ds_read_b128 v[190:193], v190 offset:3072
	s_add_u32 s2, s4, s40
	s_addc_u32 s3, s5, 0
	s_mov_b32 m0, s30
	v_lshl_add_u64 v[248:249], s[2:3], 0, v[138:139]
	ds_read_b128 v[194:197], v161 offset:32768
	ds_read_b128 v[198:201], v161 offset:33792
	ds_read_b128 v[202:205], v161 offset:34816
	ds_read_b128 v[212:215], v161 offset:35840
	ds_read_b128 v[228:231], v161 offset:36864
	ds_read_b128 v[232:235], v161 offset:37888
	ds_read_b128 v[236:239], v161 offset:38912
	ds_read_b128 v[240:243], v161 offset:39936
	global_load_lds_dwordx4 v[248:249], off
	v_lshl_add_u64 v[248:249], s[2:3], 0, v[134:135]
	s_mov_b32 m0, s31
	s_nop 0
	global_load_lds_dwordx4 v[248:249], off
	s_waitcnt vmcnt(8)
	s_waitcnt lgkmcnt(0)
	s_barrier
	s_setprio 1
	s_waitcnt lgkmcnt(0)
	v_mfma_f32_16x16x32_bf16 v[128:131], v[144:147], v[194:197], v[128:131]
	v_mfma_f32_16x16x32_bf16 v[128:131], v[166:169], v[198:201], v[128:131]
	v_mfma_f32_16x16x32_bf16 v[124:127], v[170:173], v[194:197], v[124:127]
	v_mfma_f32_16x16x32_bf16 v[124:127], v[174:177], v[198:201], v[124:127]
	v_mfma_f32_16x16x32_bf16 v[112:115], v[144:147], v[202:205], v[112:115]
	v_mfma_f32_16x16x32_bf16 v[112:115], v[166:169], v[212:215], v[112:115]
	v_mfma_f32_16x16x32_bf16 v[108:111], v[170:173], v[202:205], v[108:111]
	v_mfma_f32_16x16x32_bf16 v[108:111], v[174:177], v[212:215], v[108:111]
	v_mfma_f32_16x16x32_bf16 v[96:99], v[144:147], v[228:231], v[96:99]
	v_mfma_f32_16x16x32_bf16 v[96:99], v[166:169], v[232:235], v[96:99]
	v_mfma_f32_16x16x32_bf16 v[92:95], v[170:173], v[228:231], v[92:95]
	v_mfma_f32_16x16x32_bf16 v[92:95], v[174:177], v[232:235], v[92:95]
	v_mfma_f32_16x16x32_bf16 v[80:83], v[144:147], v[236:239], v[80:83]
	v_mfma_f32_16x16x32_bf16 v[80:83], v[166:169], v[240:243], v[80:83]
	v_mfma_f32_16x16x32_bf16 v[76:79], v[170:173], v[236:239], v[76:79]
	v_mfma_f32_16x16x32_bf16 v[76:79], v[174:177], v[240:243], v[76:79]
	s_setprio 0
	s_setprio 1
	v_mfma_f32_16x16x32_bf16 v[120:123], v[178:181], v[194:197], v[120:123]
	v_mfma_f32_16x16x32_bf16 v[120:123], v[182:185], v[198:201], v[120:123]
	v_mfma_f32_16x16x32_bf16 v[116:119], v[186:189], v[194:197], v[116:119]
	v_mfma_f32_16x16x32_bf16 v[116:119], v[190:193], v[198:201], v[116:119]
	v_mfma_f32_16x16x32_bf16 v[104:107], v[178:181], v[202:205], v[104:107]
	v_mfma_f32_16x16x32_bf16 v[104:107], v[182:185], v[212:215], v[104:107]
	v_mfma_f32_16x16x32_bf16 v[100:103], v[186:189], v[202:205], v[100:103]
	v_mfma_f32_16x16x32_bf16 v[100:103], v[190:193], v[212:215], v[100:103]
	v_mfma_f32_16x16x32_bf16 v[88:91], v[178:181], v[228:231], v[88:91]
	v_mfma_f32_16x16x32_bf16 v[88:91], v[182:185], v[232:235], v[88:91]
	v_mfma_f32_16x16x32_bf16 v[84:87], v[186:189], v[228:231], v[84:87]
	v_mfma_f32_16x16x32_bf16 v[84:87], v[190:193], v[232:235], v[84:87]
	s_setprio 2
	s_barrier
	v_mfma_f32_16x16x32_bf16 v[72:75], v[178:181], v[236:239], v[72:75]
	v_mfma_f32_16x16x32_bf16 v[72:75], v[182:185], v[240:243], v[72:75]
	v_mfma_f32_16x16x32_bf16 v[68:71], v[186:189], v[236:239], v[68:71]
	v_mfma_f32_16x16x32_bf16 v[68:71], v[190:193], v[240:243], v[68:71]
	s_setprio 0
	s_add_i32 s2, s6, s22
	v_lshl_add_u64 v[148:149], v[148:149], 0, s[86:87]
	s_mov_b32 m0, s2
	ds_read_b128 v[194:197], v161 offset:49152
	ds_read_b128 v[198:201], v161 offset:50176
	ds_read_b128 v[202:205], v161 offset:51200
	ds_read_b128 v[212:215], v161 offset:52224
	ds_read_b128 v[228:231], v161 offset:53248
	ds_read_b128 v[232:235], v161 offset:54272
	ds_read_b128 v[236:239], v161 offset:55296
	ds_read_b128 v[240:243], v161 offset:56320
	global_load_lds_dwordx4 v[148:149], off
	v_lshl_add_u64 v[148:149], v[216:217], 0, s[86:87]
	s_add_i32 m0, s2, 0x2000
	s_add_i32 s2, s7, s22
	global_load_lds_dwordx4 v[148:149], off
	v_lshl_add_u64 v[148:149], v[218:219], 0, s[86:87]
	s_mov_b32 m0, s2
	s_nop 0
	global_load_lds_dwordx4 v[148:149], off
	v_lshl_add_u64 v[148:149], v[220:221], 0, s[86:87]
	s_add_i32 m0, s2, 0x2000
	s_nop 0
	global_load_lds_dwordx4 v[148:149], off
	v_lshl_add_u64 v[148:149], v[244:245], 0, s[86:87]
	s_mov_b32 m0, s34
	s_nop 0
	global_load_lds_dwordx4 v[148:149], off
	v_lshl_add_u64 v[148:149], v[246:247], 0, s[86:87]
	s_mov_b32 m0, s35
	s_nop 0
	global_load_lds_dwordx4 v[148:149], off
	s_waitcnt vmcnt(8)
	s_waitcnt lgkmcnt(0)
	s_barrier
	s_setprio 1
	s_waitcnt lgkmcnt(0)
	v_mfma_f32_16x16x32_bf16 v[64:67], v[144:147], v[194:197], v[64:67]
	v_mfma_f32_16x16x32_bf16 v[64:67], v[166:169], v[198:201], v[64:67]
	v_mfma_f32_16x16x32_bf16 v[60:63], v[170:173], v[194:197], v[60:63]
	v_mfma_f32_16x16x32_bf16 v[60:63], v[174:177], v[198:201], v[60:63]
	v_mfma_f32_16x16x32_bf16 v[48:51], v[144:147], v[202:205], v[48:51]
	v_mfma_f32_16x16x32_bf16 v[48:51], v[166:169], v[212:215], v[48:51]
	v_mfma_f32_16x16x32_bf16 v[44:47], v[170:173], v[202:205], v[44:47]
	v_mfma_f32_16x16x32_bf16 v[44:47], v[174:177], v[212:215], v[44:47]
	v_mfma_f32_16x16x32_bf16 v[32:35], v[144:147], v[228:231], v[32:35]
	v_mfma_f32_16x16x32_bf16 v[32:35], v[166:169], v[232:235], v[32:35]
	v_mfma_f32_16x16x32_bf16 v[28:31], v[170:173], v[228:231], v[28:31]
	v_mfma_f32_16x16x32_bf16 v[28:31], v[174:177], v[232:235], v[28:31]
	v_mfma_f32_16x16x32_bf16 v[16:19], v[144:147], v[236:239], v[16:19]
	v_mfma_f32_16x16x32_bf16 v[16:19], v[166:169], v[240:243], v[16:19]
	v_mfma_f32_16x16x32_bf16 v[12:15], v[170:173], v[236:239], v[12:15]
	v_mfma_f32_16x16x32_bf16 v[12:15], v[174:177], v[240:243], v[12:15]
	s_setprio 0
	s_setprio 1
	v_mfma_f32_16x16x32_bf16 v[56:59], v[178:181], v[194:197], v[56:59]
	v_mfma_f32_16x16x32_bf16 v[56:59], v[182:185], v[198:201], v[56:59]
	v_mfma_f32_16x16x32_bf16 v[52:55], v[186:189], v[194:197], v[52:55]
	v_mfma_f32_16x16x32_bf16 v[52:55], v[190:193], v[198:201], v[52:55]
	v_mfma_f32_16x16x32_bf16 v[40:43], v[178:181], v[202:205], v[40:43]
	v_mfma_f32_16x16x32_bf16 v[40:43], v[182:185], v[212:215], v[40:43]
	v_mfma_f32_16x16x32_bf16 v[36:39], v[186:189], v[202:205], v[36:39]
	v_mfma_f32_16x16x32_bf16 v[36:39], v[190:193], v[212:215], v[36:39]
	v_mfma_f32_16x16x32_bf16 v[24:27], v[178:181], v[228:231], v[24:27]
	v_mfma_f32_16x16x32_bf16 v[24:27], v[182:185], v[232:235], v[24:27]
	v_mfma_f32_16x16x32_bf16 v[20:23], v[186:189], v[228:231], v[20:23]
	v_mfma_f32_16x16x32_bf16 v[20:23], v[190:193], v[232:235], v[20:23]
	s_setprio 2
	s_barrier
	v_mfma_f32_16x16x32_bf16 v[6:9], v[178:181], v[236:239], v[6:9]
	v_mfma_f32_16x16x32_bf16 v[6:9], v[182:185], v[240:243], v[6:9]
	v_mfma_f32_16x16x32_bf16 v[2:5], v[186:189], v[236:239], v[2:5]
	v_mfma_f32_16x16x32_bf16 v[2:5], v[190:193], v[240:243], v[2:5]
	s_setprio 0
	s_add_u32 s0, s0, 0x100
	s_addc_u32 s1, s1, 0
	s_add_u32 s47, s47, 0x100
	s_addc_u32 s49, s49, 0
	s_cmp_ge_u32 s58, s54
	s_mov_b32 s2, s58
	s_cbranch_scc0 .LBB0_2857
	s_and_b64 vcc, exec, s[44:45]
	s_cbranch_vccz .LBB0_2860
	s_barrier
